# 50 UP helpers (7 per remote XCD + tiles 4..6)
# speedup vs baseline: 1.0053x; 1.0053x over previous
; DI const bf16_t* wp(const Params& p, int l, size_t off) { return (const bf16_t*)(p.ws + OFF_WP) + (size_t)l * PW_LAYER + off; }
; template <int MT> DI void phaseB(const Params& p, int l, int t, unsigned char* lds) {
;     ...
;     EpiUp<MT> eu; eu.priv = priv; eu.d2 = d2;
;     eu.halo = (float*)(ws + OFF_UHALO) + (size_t)t * 2 * DFF2;
;     eu.pconv = t == NTILE - 1 ? p.out + O_PCONV + (size_t)l * 2 * DFF2 : nullptr;
;     eu.sconv = p.out + O_SCONV + ((size_t)l * 8 + 2 * t) * 2 * DFF2;
;     gemm64<1024, MT>(xb, DM, d2, wp(p, l, PW_UP), DFF2 / UW, lds, eu);
.LBB0_705:
	v_readlane_b32 s0, v254, 57
	s_nop 3
	s_cmp_lt_u32 s0, 4
	s_cbranch_scc1 .Lhu_done
	s_cmp_lt_u32 s0, 4
	s_cbranch_scc1 .Lhu_sel
	s_and_b32 s0, s0, 31
	s_cmp_gt_u32 s0, 6
	s_cbranch_scc1 .Lhu_done
